# RG-LRU passes: hardware v_sqrt_f32 used directly instead of the compiler's denormal-scaled two-step refined sqrtf expansion (32 sites, ~21 issue slots each)
# speedup vs baseline: 1.0092x; 1.0092x over previous
.LBB0_94:
	s_lshl_b32 s0, s21, 7
	s_add_i32 s26, s0, s77
	s_cmp_gt_i32 s26, 2
	v_lshlrev_b32_e32 v68, 16, v206
	s_cselect_b64 vcc, -1, 0
	s_cmp_gt_i32 s26, 1
	v_cndmask_b32_e32 v68, 0, v68, vcc
	v_lshlrev_b32_e32 v69, 16, v205
	s_cselect_b64 vcc, -1, 0
	s_cmp_gt_i32 s26, 0
	v_cndmask_b32_e32 v69, 0, v69, vcc
	v_lshlrev_b32_e32 v204, 16, v204
	s_cselect_b64 vcc, -1, 0
	s_cmp_gt_i32 s26, -1
	v_cndmask_b32_e32 v204, 0, v204, vcc
	v_lshlrev_b32_e32 v203, 16, v203
	s_cselect_b64 vcc, -1, 0
	s_cmp_gt_i32 s26, -2
	v_cndmask_b32_e32 v203, 0, v203, vcc
	v_lshlrev_b32_e32 v202, 16, v202
	s_cselect_b64 vcc, -1, 0
	s_cmp_gt_i32 s26, -3
	v_cndmask_b32_e32 v202, 0, v202, vcc
	v_lshlrev_b32_e32 v201, 16, v201
	s_cselect_b64 vcc, -1, 0
	s_cmp_gt_i32 s26, -4
	v_cndmask_b32_e32 v201, 0, v201, vcc
	v_lshlrev_b32_e32 v200, 16, v200
	s_cselect_b64 vcc, -1, 0
	s_cmp_gt_i32 s26, -5
	v_cndmask_b32_e32 v200, 0, v200, vcc
	v_lshlrev_b32_e32 v199, 16, v199
	s_cselect_b64 vcc, -1, 0
	s_cmp_gt_i32 s26, -6
	v_cndmask_b32_e32 v206, 0, v199, vcc
	v_lshlrev_b32_e32 v198, 16, v198
	s_cselect_b64 vcc, -1, 0
	s_cmp_gt_i32 s26, -7
	v_cndmask_b32_e32 v198, 0, v198, vcc
	v_lshlrev_b32_e32 v197, 16, v197
	s_cselect_b64 vcc, -1, 0
	s_cmp_gt_i32 s26, -8
	v_cndmask_b32_e32 v197, 0, v197, vcc
	v_lshlrev_b32_e32 v196, 16, v196
	s_cselect_b64 vcc, -1, 0
	s_cmp_gt_i32 s26, -9
	v_cndmask_b32_e32 v209, 0, v196, vcc
	v_lshlrev_b32_e32 v195, 16, v195
	s_cselect_b64 vcc, -1, 0
	s_cmp_gt_i32 s26, -10
	v_cndmask_b32_e32 v195, 0, v195, vcc
	v_lshlrev_b32_e32 v194, 16, v194
	s_cselect_b64 vcc, -1, 0
	s_cmp_gt_i32 s26, -11
	v_cndmask_b32_e32 v194, 0, v194, vcc
	v_lshlrev_b32_e32 v193, 16, v193
	s_cselect_b64 vcc, -1, 0
	s_cmp_gt_i32 s26, -12
	v_cndmask_b32_e32 v210, 0, v193, vcc
	v_lshlrev_b32_e32 v192, 16, v192
	s_cselect_b64 vcc, -1, 0
	s_cmp_gt_i32 s26, -13
	v_cndmask_b32_e32 v211, 0, v192, vcc
	v_lshlrev_b32_e32 v191, 16, v191
	s_cselect_b64 vcc, -1, 0
	s_cmp_gt_i32 s26, -14
	v_cndmask_b32_e32 v191, 0, v191, vcc
	v_lshlrev_b32_e32 v190, 16, v190
	s_cselect_b64 vcc, -1, 0
	v_fma_f32 v226, v68, v81, v117
	v_cndmask_b32_e32 v212, 0, v190, vcc
	v_fmac_f32_e32 v226, v69, v114
	v_fma_f32 v190, v69, v81, v117
	v_fmac_f32_e32 v226, v204, v115
	v_fmac_f32_e32 v190, v204, v114
	v_fma_f32 v193, v204, v81, v117
	v_fmac_f32_e32 v226, v203, v116
	v_cvt_pk_bf16_f32 v68, v226, v129
	v_fmac_f32_e32 v190, v203, v115
	v_fmac_f32_e32 v193, v203, v114
	v_fma_f32 v196, v203, v81, v117
	ds_write_b16 v72, v68
	v_fmac_f32_e32 v190, v202, v116
	v_cvt_pk_bf16_f32 v68, v190, v129
	v_fmac_f32_e32 v193, v202, v115
	v_fmac_f32_e32 v196, v202, v114
	v_fma_f32 v199, v202, v81, v117
	ds_write_b16 v72, v68 offset:144
	v_fmac_f32_e32 v193, v201, v116
	v_cvt_pk_bf16_f32 v68, v193, v129
	v_fmac_f32_e32 v196, v201, v115
	v_fmac_f32_e32 v199, v201, v114
	v_fma_f32 v202, v201, v81, v117
	ds_write_b16 v72, v68 offset:288
	v_fmac_f32_e32 v196, v200, v116
	v_cvt_pk_bf16_f32 v68, v196, v129
	v_fmac_f32_e32 v199, v200, v115
	v_fmac_f32_e32 v202, v200, v114
	v_fma_f32 v205, v200, v81, v117
	ds_write_b16 v72, v68 offset:432
	v_fmac_f32_e32 v199, v206, v116
	v_cvt_pk_bf16_f32 v68, v199, v129
	v_fmac_f32_e32 v202, v206, v115
	v_fmac_f32_e32 v205, v206, v114
	v_fma_f32 v208, v206, v81, v117
	ds_write_b16 v72, v68 offset:576
	v_fmac_f32_e32 v202, v198, v116
	v_cvt_pk_bf16_f32 v68, v202, v129
	v_fmac_f32_e32 v205, v198, v115
	v_fmac_f32_e32 v208, v198, v114
	v_fma_f32 v207, v198, v81, v117
	ds_write_b16 v72, v68 offset:720
	v_fmac_f32_e32 v205, v197, v116
	v_cvt_pk_bf16_f32 v68, v205, v129
	v_fmac_f32_e32 v208, v197, v115
	v_fmac_f32_e32 v207, v197, v114
	v_fma_f32 v204, v197, v81, v117
	ds_write_b16 v72, v68 offset:864
	v_fmac_f32_e32 v208, v209, v116
	v_cvt_pk_bf16_f32 v68, v208, v129
	v_fmac_f32_e32 v207, v209, v115
	v_fmac_f32_e32 v204, v209, v114
	v_fma_f32 v201, v209, v81, v117
	ds_write_b16 v72, v68 offset:1008
	v_fmac_f32_e32 v207, v195, v116
	v_cvt_pk_bf16_f32 v68, v207, v129
	v_fmac_f32_e32 v204, v195, v115
	v_fmac_f32_e32 v201, v195, v114
	v_fma_f32 v198, v195, v81, v117
	ds_write_b16 v72, v68 offset:1152
	v_fmac_f32_e32 v204, v194, v116
	v_cvt_pk_bf16_f32 v68, v204, v129
	v_fmac_f32_e32 v201, v194, v115
	v_fmac_f32_e32 v198, v194, v114
	v_fma_f32 v195, v194, v81, v117
	ds_write_b16 v72, v68 offset:1296
	v_fmac_f32_e32 v201, v210, v116
	v_cvt_pk_bf16_f32 v68, v201, v129
	v_fmac_f32_e32 v198, v210, v115
	v_fmac_f32_e32 v195, v210, v114
	v_fma_f32 v192, v210, v81, v117
	s_cmp_gt_i32 s26, -15
	ds_write_b16 v72, v68 offset:1440
	v_fmac_f32_e32 v198, v211, v116
	v_cvt_pk_bf16_f32 v68, v198, v129
	v_fmac_f32_e32 v195, v211, v115
	v_fmac_f32_e32 v192, v211, v114
	v_fma_f32 v69, v211, v81, v117
	v_lshlrev_b32_e32 v189, 16, v189
	s_cselect_b64 vcc, -1, 0
	ds_write_b16 v72, v68 offset:1584
	v_fmac_f32_e32 v195, v191, v116
	v_cvt_pk_bf16_f32 v68, v195, v129
	v_fmac_f32_e32 v192, v191, v115
	v_fmac_f32_e32 v69, v191, v114
	v_cndmask_b32_e32 v189, 0, v189, vcc
	ds_write_b16 v72, v68 offset:1728
	v_fmac_f32_e32 v192, v212, v116
	v_cvt_pk_bf16_f32 v68, v192, v129
	v_fmac_f32_e32 v69, v212, v115
	ds_write_b16 v72, v68 offset:1872
	v_fmac_f32_e32 v69, v189, v116
	v_cvt_pk_bf16_f32 v68, v69, v129
	s_cmp_gt_i32 s26, -16
	ds_write_b16 v72, v68 offset:2016
	v_fma_f32 v68, v191, v81, v117
	v_lshlrev_b32_e32 v188, 16, v188
	s_cselect_b64 vcc, -1, 0
	v_fmac_f32_e32 v68, v212, v114
	v_cndmask_b32_e32 v188, 0, v188, vcc
	v_fmac_f32_e32 v68, v189, v115
	v_fmac_f32_e32 v68, v188, v116
	v_cvt_pk_bf16_f32 v188, v68, v129
	ds_write_b16 v72, v188 offset:2160
	s_waitcnt lgkmcnt(0)
	ds_read_b128 v[210:213], v112
	ds_read_b128 v[214:217], v112 offset:64
	s_waitcnt lgkmcnt(0)
	v_mfma_f32_16x16x32_bf16 v[218:221], v[210:213], v[0:3], 0
	v_add_u32_e32 v188, 0x800, v113
	v_add_u32_e32 v189, 0xc00, v113
	v_mfma_f32_16x16x32_bf16 v[222:225], v[210:213], v[8:11], 0
	v_mfma_f32_16x16x32_bf16 v[218:221], v[214:217], v[4:7], v[218:221]
	v_mfma_f32_16x16x32_bf16 v[222:225], v[214:217], v[12:15], v[222:225]
	s_nop 7
	ds_write2_b32 v188, v218, v222 offset0:64 offset1:80
	ds_write2_b32 v188, v219, v223 offset0:132 offset1:148
	ds_write2_b32 v188, v220, v224 offset0:200 offset1:216
	ds_write2_b32 v189, v221, v225 offset0:12 offset1:28
	v_mfma_f32_16x16x32_bf16 v[218:221], v[210:213], v[16:19], 0
	v_mfma_f32_16x16x32_bf16 v[222:225], v[210:213], v[24:27], 0
	v_mfma_f32_16x16x32_bf16 v[218:221], v[214:217], v[20:23], v[218:221]
	v_mfma_f32_16x16x32_bf16 v[222:225], v[214:217], v[28:31], v[222:225]
	s_nop 7
	ds_write2_b32 v188, v218, v222 offset0:96 offset1:112
	ds_write2_b32 v188, v219, v223 offset0:164 offset1:180
	ds_write2_b32 v188, v220, v224 offset0:232 offset1:248
	ds_write2_b32 v189, v221, v225 offset0:44 offset1:60
	v_mfma_f32_16x16x32_bf16 v[218:221], v[210:213], v[32:35], 0
	v_add_u32_e32 v188, 0x1800, v113
	v_add_u32_e32 v189, 0x1c00, v113
	v_mfma_f32_16x16x32_bf16 v[222:225], v[210:213], v[40:43], 0
	v_mfma_f32_16x16x32_bf16 v[218:221], v[214:217], v[36:39], v[218:221]
	v_mfma_f32_16x16x32_bf16 v[222:225], v[214:217], v[44:47], v[222:225]
	s_nop 7
	ds_write2_b32 v188, v218, v222 offset0:128 offset1:144
	ds_write2_b32 v188, v219, v223 offset0:196 offset1:212
	ds_write2_b32 v189, v220, v224 offset0:8 offset1:24
	ds_write2_b32 v189, v221, v225 offset0:76 offset1:92
	v_mfma_f32_16x16x32_bf16 v[218:221], v[210:213], v[48:51], 0
	v_mfma_f32_16x16x32_bf16 v[210:213], v[210:213], v[56:59], 0
	v_mfma_f32_16x16x32_bf16 v[218:221], v[214:217], v[52:55], v[218:221]
	v_mfma_f32_16x16x32_bf16 v[210:213], v[214:217], v[60:63], v[210:213]
	s_nop 7
	ds_write2_b32 v188, v218, v210 offset0:160 offset1:176
	ds_write2_b32 v188, v219, v211 offset0:228 offset1:244
	ds_write2_b32 v189, v220, v212 offset0:40 offset1:56
	ds_write2_b32 v189, v221, v213 offset0:108 offset1:124
	s_waitcnt lgkmcnt(0)
	v_add_u32_e32 v188, 0x800, v73
	ds_read2_b32 v[210:211], v188 offset0:64 offset1:132
	v_add_u32_e32 v189, 0x1800, v73
	ds_read2_b32 v[212:213], v189 offset0:128 offset1:196
	v_add_u32_e32 v214, 0x2000, v73
	s_waitcnt lgkmcnt(1)
	v_fmamk_f32 v188, v210, 0xbfb8aa3b, v131
	v_exp_f32_e32 v188, v188
	s_waitcnt lgkmcnt(0)
	v_fmamk_f32 v189, v212, 0xbfb8aa3b, v67
	v_exp_f32_e32 v189, v189
	v_add_f32_e32 v188, 1.0, v188
	v_rcp_f32_e32 v188, v188
	v_add_f32_e32 v189, 1.0, v189
	v_rcp_f32_e32 v189, v189
	v_mul_f32_e32 v188, v66, v188
	v_exp_f32_e32 v188, v188
	s_nop 0
	v_fma_f32 v191, -v188, v188, 1.0
	v_max_f32_e32 v191, 0, v191
	v_sqrt_f32_e32 v191, v191
	s_nop 0
	v_mul_f32_e32 v189, v189, v191
	v_fmamk_f32 v191, v211, 0xbfb8aa3b, v131
	v_exp_f32_e32 v191, v191
	v_fmamk_f32 v194, v213, 0xbfb8aa3b, v67
	v_exp_f32_e32 v194, v194
	v_mul_f32_e32 v189, v226, v189
	v_add_f32_e32 v191, 1.0, v191
	v_rcp_f32_e32 v191, v191
	v_add_f32_e32 v194, 1.0, v194
	v_rcp_f32_e32 v194, v194
	v_fmac_f32_e32 v189, 0, v188
	v_mul_f32_e32 v191, v66, v191
	v_exp_f32_e32 v191, v191
	s_nop 0
	v_fma_f32 v197, -v191, v191, 1.0
	v_max_f32_e32 v197, 0, v197
	v_sqrt_f32_e32 v197, v197
	s_nop 0
	v_mul_f32_e32 v194, v194, v197
	v_mul_f32_e32 v190, v190, v194
	v_add_u32_e32 v194, 0xa00, v73
	ds_read2_b32 v[210:211], v194 offset0:72 offset1:140
	v_add_u32_e32 v200, 0x1c00, v73
	ds_read2_b32 v[212:213], v200 offset0:8 offset1:76
	v_fmac_f32_e32 v190, v191, v189
	v_mul_f32_e32 v191, v188, v191
	s_waitcnt lgkmcnt(1)
	v_fmamk_f32 v194, v210, 0xbfb8aa3b, v131
	v_exp_f32_e32 v194, v194
	s_waitcnt lgkmcnt(0)
	v_fmamk_f32 v197, v212, 0xbfb8aa3b, v67
	v_exp_f32_e32 v197, v197
	v_add_f32_e32 v194, 1.0, v194
	v_rcp_f32_e32 v194, v194
	v_add_f32_e32 v197, 1.0, v197
	v_rcp_f32_e32 v197, v197
	v_mul_f32_e32 v194, v66, v194
	v_exp_f32_e32 v194, v194
	s_nop 0
	v_fma_f32 v203, -v194, v194, 1.0
	v_max_f32_e32 v203, 0, v203
	v_sqrt_f32_e32 v203, v203
	s_nop 0
	v_mul_f32_e32 v197, v197, v203
	v_mul_f32_e32 v193, v193, v197
	v_fmamk_f32 v197, v211, 0xbfb8aa3b, v131
	v_exp_f32_e32 v197, v197
	v_fmamk_f32 v203, v213, 0xbfb8aa3b, v67
	v_exp_f32_e32 v203, v203
	ds_read2_b32 v[212:213], v200 offset0:144 offset1:212
	v_add_f32_e32 v197, 1.0, v197
	v_rcp_f32_e32 v197, v197
	v_add_f32_e32 v203, 1.0, v203
	v_rcp_f32_e32 v203, v203
	s_waitcnt lgkmcnt(0)
	v_fmamk_f32 v200, v212, 0xbfb8aa3b, v67
	v_mul_f32_e32 v197, v66, v197
	v_exp_f32_e32 v197, v197
	v_exp_f32_e32 v200, v200
	v_fmac_f32_e32 v193, v194, v190
	v_mul_f32_e32 v194, v191, v194
	v_fma_f32 v206, -v197, v197, 1.0
	v_max_f32_e32 v206, 0, v206
	v_add_f32_e32 v200, 1.0, v200
	v_sqrt_f32_e32 v206, v206
	s_nop 0
	v_rcp_f32_e32 v200, v200
	s_nop 0
	v_mul_f32_e32 v203, v203, v206
	v_mul_f32_e32 v196, v196, v203
	v_add_u32_e32 v203, 0xc00, v73
	ds_read2_b32 v[210:211], v203 offset0:80 offset1:148
	v_fmac_f32_e32 v196, v197, v193
	v_mul_f32_e32 v197, v194, v197
	s_waitcnt lgkmcnt(0)
	v_fmamk_f32 v203, v210, 0xbfb8aa3b, v131
	v_exp_f32_e32 v203, v203
	s_nop 0
	v_add_f32_e32 v203, 1.0, v203
	v_rcp_f32_e32 v203, v203
	s_nop 0
	v_mul_f32_e32 v203, v66, v203
	v_exp_f32_e32 v203, v203
	s_nop 0
	v_fma_f32 v206, -v203, v203, 1.0
	v_max_f32_e32 v206, 0, v206
	v_sqrt_f32_e32 v206, v206
	s_nop 0
	v_mul_f32_e32 v200, v200, v206
	v_mul_f32_e32 v199, v199, v200
	v_fmac_f32_e32 v199, v203, v196
	v_mul_f32_e32 v200, v197, v203
	v_fmamk_f32 v203, v211, 0xbfb8aa3b, v131
	v_exp_f32_e32 v203, v203
	v_fmamk_f32 v206, v213, 0xbfb8aa3b, v67
	v_exp_f32_e32 v206, v206
	v_add_f32_e32 v203, 1.0, v203
	v_rcp_f32_e32 v203, v203
	v_add_f32_e32 v206, 1.0, v206
	v_rcp_f32_e32 v206, v206
	v_mul_f32_e32 v203, v66, v203
	v_exp_f32_e32 v203, v203
	s_nop 0
	v_fma_f32 v209, -v203, v203, 1.0
	v_max_f32_e32 v209, 0, v209
	v_sqrt_f32_e32 v209, v209
	s_nop 0
	ds_read2_b32 v[212:213], v214 offset0:24 offset1:92
	v_mul_f32_e32 v206, v206, v209
	v_mul_f32_e32 v202, v202, v206
	v_add_u32_e32 v206, 0xe00, v73
	ds_read2_b32 v[210:211], v206 offset0:88 offset1:156
	s_waitcnt lgkmcnt(1)
	v_fmamk_f32 v209, v212, 0xbfb8aa3b, v67
	v_exp_f32_e32 v209, v209
	v_fmac_f32_e32 v202, v203, v199
	v_mul_f32_e32 v203, v200, v203
	s_waitcnt lgkmcnt(0)
	v_fmamk_f32 v206, v210, 0xbfb8aa3b, v131
	v_exp_f32_e32 v206, v206
	v_add_f32_e32 v209, 1.0, v209
	v_rcp_f32_e32 v209, v209
	v_add_f32_e32 v206, 1.0, v206
	v_rcp_f32_e32 v206, v206
	s_nop 0
	v_mul_f32_e32 v206, v66, v206
	v_exp_f32_e32 v206, v206
	s_nop 0
	v_fma_f32 v210, -v206, v206, 1.0
	v_max_f32_e32 v210, 0, v210
	v_sqrt_f32_e32 v210, v210
	s_nop 0
	v_mul_f32_e32 v209, v209, v210
	v_mul_f32_e32 v205, v205, v209
	v_fmamk_f32 v209, v211, 0xbfb8aa3b, v131
	v_exp_f32_e32 v209, v209
	v_fmamk_f32 v210, v213, 0xbfb8aa3b, v67
	v_exp_f32_e32 v210, v210
	v_fmac_f32_e32 v205, v206, v202
	v_add_f32_e32 v209, 1.0, v209
	v_rcp_f32_e32 v209, v209
	v_add_f32_e32 v210, 1.0, v210
	v_rcp_f32_e32 v210, v210
	v_mul_f32_e32 v206, v203, v206
	v_mul_f32_e32 v209, v66, v209
	v_exp_f32_e32 v209, v209
	s_nop 0
	v_fma_f32 v211, -v209, v209, 1.0
	v_max_f32_e32 v211, 0, v211
	v_sqrt_f32_e32 v211, v211
	s_nop 0
	v_mul_f32_e32 v210, v210, v211
	v_mul_f32_e32 v208, v208, v210
	v_add_u32_e32 v210, 0x1000, v73
	ds_read2_b32 v[210:211], v210 offset0:96 offset1:164
	ds_read2_b32 v[212:213], v214 offset0:160 offset1:228
	v_fmac_f32_e32 v208, v209, v205
	v_mul_f32_e32 v209, v206, v209
	s_waitcnt lgkmcnt(1)
	v_fmamk_f32 v210, v210, 0xbfb8aa3b, v131
	v_exp_f32_e32 v210, v210
	v_fmamk_f32 v211, v211, 0xbfb8aa3b, v131
	v_exp_f32_e32 v211, v211
	s_waitcnt lgkmcnt(0)
	v_fmamk_f32 v212, v212, 0xbfb8aa3b, v67
	v_add_f32_e32 v210, 1.0, v210
	v_rcp_f32_e32 v210, v210
	v_exp_f32_e32 v212, v212
	v_add_f32_e32 v211, 1.0, v211
	v_rcp_f32_e32 v211, v211
	v_mul_f32_e32 v210, v66, v210
	v_exp_f32_e32 v210, v210
	v_add_f32_e32 v212, 1.0, v212
	v_rcp_f32_e32 v212, v212
	v_mul_f32_e32 v211, v66, v211
	v_fma_f32 v214, -v210, v210, 1.0
	v_max_f32_e32 v214, 0, v214
	v_exp_f32_e32 v211, v211
	s_nop 0
	v_sqrt_f32_e32 v214, v214
	s_nop 0
	v_mul_f32_e32 v212, v212, v214
	v_mul_f32_e32 v207, v207, v212
	v_fmamk_f32 v212, v213, 0xbfb8aa3b, v67
	v_fma_f32 v213, -v211, v211, 1.0
	v_max_f32_e32 v213, 0, v213
	v_exp_f32_e32 v212, v212
	s_nop 0
	v_sqrt_f32_e32 v213, v213
	s_nop 0
	v_fmac_f32_e32 v207, v210, v208
	v_add_f32_e32 v212, 1.0, v212
	v_rcp_f32_e32 v212, v212
	s_nop 0
	v_mul_f32_e32 v210, v209, v210
	v_add_u32_e32 v216, 0x2400, v73
	v_mul_f32_e32 v212, v212, v213
	v_mul_f32_e32 v204, v204, v212
	v_add_u32_e32 v212, 0x1200, v73
	ds_read2_b32 v[212:213], v212 offset0:104 offset1:172
	ds_read2_b32 v[214:215], v216 offset0:40 offset1:108
	v_fmac_f32_e32 v204, v211, v207
	v_mul_f32_e32 v211, v210, v211
	s_waitcnt lgkmcnt(1)
	v_fmamk_f32 v212, v212, 0xbfb8aa3b, v131
	v_exp_f32_e32 v212, v212
	v_fmamk_f32 v213, v213, 0xbfb8aa3b, v131
	v_exp_f32_e32 v213, v213
	s_waitcnt lgkmcnt(0)
	v_fmamk_f32 v214, v214, 0xbfb8aa3b, v67
	v_add_f32_e32 v212, 1.0, v212
	v_rcp_f32_e32 v212, v212
	v_exp_f32_e32 v214, v214
	v_add_f32_e32 v213, 1.0, v213
	v_rcp_f32_e32 v213, v213
	v_mul_f32_e32 v212, v66, v212
	v_exp_f32_e32 v212, v212
	v_add_f32_e32 v214, 1.0, v214
	v_rcp_f32_e32 v214, v214
	v_mul_f32_e32 v213, v66, v213
	v_fma_f32 v217, -v212, v212, 1.0
	v_max_f32_e32 v217, 0, v217
	v_exp_f32_e32 v213, v213
	s_nop 0
	v_sqrt_f32_e32 v217, v217
	s_nop 0
	v_mul_f32_e32 v214, v214, v217
	v_mul_f32_e32 v201, v201, v214
	v_fmamk_f32 v214, v215, 0xbfb8aa3b, v67
	v_fma_f32 v215, -v213, v213, 1.0
	v_max_f32_e32 v215, 0, v215
	v_exp_f32_e32 v214, v214
	s_nop 0
	v_sqrt_f32_e32 v215, v215
	s_nop 0
	v_fmac_f32_e32 v201, v212, v204
	v_add_f32_e32 v214, 1.0, v214
	v_rcp_f32_e32 v214, v214
	s_nop 0
	v_mul_f32_e32 v212, v211, v212
	v_mul_f32_e32 v214, v214, v215
	v_mul_f32_e32 v198, v198, v214
	v_add_u32_e32 v214, 0x1400, v73
	ds_read2_b32 v[214:215], v214 offset0:112 offset1:180
	ds_read2_b32 v[216:217], v216 offset0:176 offset1:244
	v_fmac_f32_e32 v198, v213, v201
	v_mul_f32_e32 v213, v212, v213
	s_waitcnt lgkmcnt(1)
	v_fmamk_f32 v214, v214, 0xbfb8aa3b, v131
	v_exp_f32_e32 v214, v214
	v_fmamk_f32 v215, v215, 0xbfb8aa3b, v131
	v_exp_f32_e32 v215, v215
	s_waitcnt lgkmcnt(0)
	v_fmamk_f32 v216, v216, 0xbfb8aa3b, v67
	v_add_f32_e32 v214, 1.0, v214
	v_rcp_f32_e32 v214, v214
	v_exp_f32_e32 v216, v216
	v_add_f32_e32 v215, 1.0, v215
	v_rcp_f32_e32 v215, v215
	v_mul_f32_e32 v214, v66, v214
	v_exp_f32_e32 v214, v214
	v_add_f32_e32 v216, 1.0, v216
	v_rcp_f32_e32 v216, v216
	v_mul_f32_e32 v215, v66, v215
	v_fma_f32 v218, -v214, v214, 1.0
	v_max_f32_e32 v218, 0, v218
	v_exp_f32_e32 v215, v215
	s_nop 0
	v_sqrt_f32_e32 v218, v218
	s_nop 0
	v_mul_f32_e32 v216, v216, v218
	v_mul_f32_e32 v195, v195, v216
	v_fmamk_f32 v216, v217, 0xbfb8aa3b, v67
	v_fma_f32 v217, -v215, v215, 1.0
	v_max_f32_e32 v217, 0, v217
	v_exp_f32_e32 v216, v216
	s_nop 0
	v_sqrt_f32_e32 v217, v217
	s_nop 0
	v_fmac_f32_e32 v195, v214, v198
	v_add_f32_e32 v216, 1.0, v216
	v_rcp_f32_e32 v216, v216
	s_nop 0
	v_mul_f32_e32 v214, v213, v214
	v_mul_f32_e32 v216, v216, v217
	v_mul_f32_e32 v192, v192, v216
	v_add_u32_e32 v216, 0x1600, v73
	ds_read2_b32 v[218:219], v216 offset0:120 offset1:188
	v_add_u32_e32 v217, 0x2800, v73
	ds_read2_b32 v[220:221], v217 offset0:56 offset1:124
	v_fmac_f32_e32 v192, v215, v195
	v_mul_f32_e32 v215, v214, v215
	s_waitcnt lgkmcnt(1)
	v_fmamk_f32 v216, v218, 0xbfb8aa3b, v131
	v_exp_f32_e32 v216, v216
	s_waitcnt lgkmcnt(0)
	v_fmamk_f32 v217, v220, 0xbfb8aa3b, v67
	v_exp_f32_e32 v217, v217
	v_add_f32_e32 v216, 1.0, v216
	v_rcp_f32_e32 v216, v216
	v_add_f32_e32 v217, 1.0, v217
	v_rcp_f32_e32 v217, v217
	v_mul_f32_e32 v216, v66, v216
	v_exp_f32_e32 v218, v216
	s_nop 0
	v_fma_f32 v216, -v218, v218, 1.0
	v_max_f32_e32 v216, 0, v216
	v_sqrt_f32_e32 v216, v216
	s_nop 0
	v_mul_f32_e32 v216, v217, v216
	v_mul_f32_e32 v216, v69, v216
	v_fmamk_f32 v69, v219, 0xbfb8aa3b, v131
	v_exp_f32_e32 v69, v69
	v_fmac_f32_e32 v216, v218, v192
	v_mul_f32_e32 v217, v215, v218
	v_fmamk_f32 v218, v221, 0xbfb8aa3b, v67
	v_add_f32_e32 v69, 1.0, v69
	v_rcp_f32_e32 v69, v69
	v_exp_f32_e32 v218, v218
	v_mul_f32_e32 v69, v66, v69
	v_exp_f32_e32 v69, v69
	v_add_f32_e32 v218, 1.0, v218
	v_rcp_f32_e32 v218, v218
	v_fma_f32 v219, -v69, v69, 1.0
	v_max_f32_e32 v219, 0, v219
	v_sqrt_f32_e32 v219, v219
	s_nop 0
	s_mov_b32 s0, s91
	v_mul_f32_e32 v218, v218, v219
	v_mul_f32_e32 v218, v68, v218
	v_fmac_f32_e32 v218, v69, v216
	v_mul_f32_e32 v219, v217, v69
	ds_write2st64_b32 v140, v219, v218 offset1:1
	s_waitcnt lgkmcnt(0)
	s_barrier
	ds_read_b32 v140, v71
	s_andn2_b64 vcc, exec, s[10:11]
	v_mov_b32_e32 v68, v74
	s_cbranch_vccnz .LBB0_96

.LBB0_127:
	s_and_b32 s17, s15, 0xf80
	s_add_i32 s0, s17, s12
	s_cmp_gt_i32 s0, 2
	v_lshlrev_b32_e32 v137, 16, v137
	s_cselect_b64 vcc, -1, 0
	s_cmp_gt_i32 s0, 1
	v_cndmask_b32_e32 v137, 0, v137, vcc
	v_lshlrev_b32_e32 v136, 16, v136
	s_cselect_b64 vcc, -1, 0
	s_cmp_gt_i32 s0, 0
	v_cndmask_b32_e32 v136, 0, v136, vcc
	v_lshlrev_b32_e32 v135, 16, v135
	s_cselect_b64 vcc, -1, 0
	s_cmp_gt_i32 s0, -1
	v_cndmask_b32_e32 v135, 0, v135, vcc
	v_lshlrev_b32_e32 v134, 16, v134
	s_cselect_b64 vcc, -1, 0
	s_cmp_gt_i32 s0, -2
	v_cndmask_b32_e32 v134, 0, v134, vcc
	v_lshlrev_b32_e32 v127, 16, v127
	s_cselect_b64 vcc, -1, 0
	s_cmp_gt_i32 s0, -3
	v_cndmask_b32_e32 v170, 0, v127, vcc
	v_lshlrev_b32_e32 v126, 16, v126
	s_cselect_b64 vcc, -1, 0
	s_cmp_gt_i32 s0, -4
	v_cndmask_b32_e32 v171, 0, v126, vcc
	v_lshlrev_b32_e32 v125, 16, v125
	s_cselect_b64 vcc, -1, 0
	s_cmp_gt_i32 s0, -5
	v_cndmask_b32_e32 v172, 0, v125, vcc
	v_lshlrev_b32_e32 v124, 16, v124
	s_cselect_b64 vcc, -1, 0
	s_cmp_gt_i32 s0, -6
	v_cndmask_b32_e32 v173, 0, v124, vcc
	v_lshlrev_b32_e32 v123, 16, v123
	s_cselect_b64 vcc, -1, 0
	s_cmp_gt_i32 s0, -7
	v_cndmask_b32_e32 v174, 0, v123, vcc
	v_lshlrev_b32_e32 v122, 16, v122
	s_cselect_b64 vcc, -1, 0
	s_cmp_gt_i32 s0, -8
	v_cndmask_b32_e32 v175, 0, v122, vcc
	v_lshlrev_b32_e32 v121, 16, v121
	s_cselect_b64 vcc, -1, 0
	s_cmp_gt_i32 s0, -9
	v_cndmask_b32_e32 v176, 0, v121, vcc
	v_lshlrev_b32_e32 v120, 16, v120
	s_cselect_b64 vcc, -1, 0
	s_cmp_gt_i32 s0, -10
	v_cndmask_b32_e32 v177, 0, v120, vcc
	v_lshlrev_b32_e32 v119, 16, v119
	s_cselect_b64 vcc, -1, 0
	s_cmp_gt_i32 s0, -11
	v_cndmask_b32_e32 v178, 0, v119, vcc
	v_lshlrev_b32_e32 v116, 16, v116
	s_cselect_b64 vcc, -1, 0
	s_cmp_gt_i32 s0, -12
	v_cndmask_b32_e32 v179, 0, v116, vcc
	v_lshlrev_b32_e32 v115, 16, v115
	s_cselect_b64 vcc, -1, 0
	s_cmp_gt_i32 s0, -13
	v_cndmask_b32_e32 v180, 0, v115, vcc
	v_lshlrev_b32_e32 v114, 16, v114
	s_cselect_b64 vcc, -1, 0
	s_cmp_gt_i32 s0, -14
	v_cndmask_b32_e32 v181, 0, v114, vcc
	v_lshlrev_b32_e32 v113, 16, v113
	s_cselect_b64 vcc, -1, 0
	s_cmp_gt_i32 s0, -15
	v_fma_f32 v185, v137, v81, v111
	v_cndmask_b32_e32 v182, 0, v113, vcc
	v_lshlrev_b32_e32 v113, 16, v118
	s_cselect_b64 vcc, -1, 0
	s_cmp_gt_i32 s0, -16
	v_fmac_f32_e32 v185, v136, v108
	v_fma_f32 v127, v136, v81, v111
	v_cndmask_b32_e32 v183, 0, v113, vcc
	v_lshlrev_b32_e32 v113, 16, v117
	s_cselect_b64 vcc, -1, 0
	v_fmac_f32_e32 v185, v135, v109
	v_fmac_f32_e32 v127, v135, v108
	v_fma_f32 v126, v135, v81, v111
	v_cndmask_b32_e32 v184, 0, v113, vcc
	v_fmac_f32_e32 v185, v134, v110
	v_cvt_pk_bf16_f32 v113, v185, v129
	v_fmac_f32_e32 v127, v134, v109
	v_fmac_f32_e32 v126, v134, v108
	v_fma_f32 v125, v134, v81, v111
	ds_write_b16 v69, v113
	v_fmac_f32_e32 v127, v170, v110
	v_cvt_pk_bf16_f32 v113, v127, v129
	v_fmac_f32_e32 v126, v170, v109
	v_fmac_f32_e32 v125, v170, v108
	v_fma_f32 v124, v170, v81, v111
	ds_write_b16 v69, v113 offset:144
	v_fmac_f32_e32 v126, v171, v110
	v_cvt_pk_bf16_f32 v113, v126, v129
	v_fmac_f32_e32 v125, v171, v109
	v_fmac_f32_e32 v124, v171, v108
	v_fma_f32 v123, v171, v81, v111
	ds_write_b16 v69, v113 offset:288
	v_fmac_f32_e32 v125, v172, v110
	v_cvt_pk_bf16_f32 v113, v125, v129
	v_fmac_f32_e32 v124, v172, v109
	v_fmac_f32_e32 v123, v172, v108
	v_fma_f32 v122, v172, v81, v111
	ds_write_b16 v69, v113 offset:432
	v_fmac_f32_e32 v124, v173, v110
	v_cvt_pk_bf16_f32 v113, v124, v129
	v_fmac_f32_e32 v123, v173, v109
	v_fmac_f32_e32 v122, v173, v108
	v_fma_f32 v121, v173, v81, v111
	ds_write_b16 v69, v113 offset:576
	v_fmac_f32_e32 v123, v174, v110
	v_cvt_pk_bf16_f32 v113, v123, v129
	v_fmac_f32_e32 v122, v174, v109
	v_fmac_f32_e32 v121, v174, v108
	v_fma_f32 v120, v174, v81, v111
	ds_write_b16 v69, v113 offset:720
	v_fmac_f32_e32 v122, v175, v110
	v_cvt_pk_bf16_f32 v113, v122, v129
	v_fmac_f32_e32 v121, v175, v109
	v_fmac_f32_e32 v120, v175, v108
	v_fma_f32 v119, v175, v81, v111
	ds_write_b16 v69, v113 offset:864
	v_fmac_f32_e32 v121, v176, v110
	v_cvt_pk_bf16_f32 v113, v121, v129
	v_fmac_f32_e32 v120, v176, v109
	v_fmac_f32_e32 v119, v176, v108
	v_fma_f32 v118, v176, v81, v111
	ds_write_b16 v69, v113 offset:1008
	v_fmac_f32_e32 v120, v177, v110
	v_cvt_pk_bf16_f32 v113, v120, v129
	v_fmac_f32_e32 v119, v177, v109
	v_fmac_f32_e32 v118, v177, v108
	v_fma_f32 v117, v177, v81, v111
	ds_write_b16 v69, v113 offset:1152
	v_fmac_f32_e32 v119, v178, v110
	v_cvt_pk_bf16_f32 v113, v119, v129
	v_fmac_f32_e32 v118, v178, v109
	v_fmac_f32_e32 v117, v178, v108
	v_fma_f32 v116, v178, v81, v111
	ds_write_b16 v69, v113 offset:1296
	v_fmac_f32_e32 v118, v179, v110
	v_cvt_pk_bf16_f32 v113, v118, v129
	v_fmac_f32_e32 v117, v179, v109
	v_fmac_f32_e32 v116, v179, v108
	v_fma_f32 v115, v179, v81, v111
	ds_write_b16 v69, v113 offset:1440
	v_fmac_f32_e32 v117, v180, v110
	v_cvt_pk_bf16_f32 v113, v117, v129
	v_fmac_f32_e32 v116, v180, v109
	v_fmac_f32_e32 v115, v180, v108
	v_fma_f32 v114, v180, v81, v111
	ds_write_b16 v69, v113 offset:1584
	v_fmac_f32_e32 v116, v181, v110
	v_cvt_pk_bf16_f32 v113, v116, v129
	v_fmac_f32_e32 v115, v181, v109
	v_fmac_f32_e32 v114, v181, v108
	ds_write_b16 v69, v113 offset:1728
	v_fmac_f32_e32 v115, v182, v110
	v_cvt_pk_bf16_f32 v113, v115, v129
	v_fmac_f32_e32 v114, v182, v109
	ds_write_b16 v69, v113 offset:1872
	v_fmac_f32_e32 v114, v183, v110
	v_cvt_pk_bf16_f32 v113, v114, v129
	ds_write_b16 v69, v113 offset:2016
	v_fma_f32 v113, v181, v81, v111
	v_fmac_f32_e32 v113, v182, v108
	v_fmac_f32_e32 v113, v183, v109
	v_fmac_f32_e32 v113, v184, v110
	v_cvt_pk_bf16_f32 v134, v113, v129
	ds_write_b16 v69, v134 offset:2160
	s_waitcnt lgkmcnt(0)
	ds_read_b128 v[134:137], v106
	ds_read_b128 v[170:173], v106 offset:64
	s_waitcnt lgkmcnt(1)
	v_mfma_f32_16x16x32_bf16 v[174:177], v[134:137], v[0:3], 0
	v_add_u32_e32 v182, 0x800, v107
	v_add_u32_e32 v183, 0xc00, v107
	v_mfma_f32_16x16x32_bf16 v[178:181], v[134:137], v[8:11], 0
	s_waitcnt lgkmcnt(0)
	v_mfma_f32_16x16x32_bf16 v[174:177], v[170:173], v[4:7], v[174:177]
	v_mfma_f32_16x16x32_bf16 v[178:181], v[170:173], v[12:15], v[178:181]
	s_nop 7
	ds_write2_b32 v182, v174, v178 offset0:64 offset1:80
	ds_write2_b32 v182, v175, v179 offset0:132 offset1:148
	ds_write2_b32 v182, v176, v180 offset0:200 offset1:216
	ds_write2_b32 v183, v177, v181 offset0:12 offset1:28
	v_mfma_f32_16x16x32_bf16 v[174:177], v[134:137], v[16:19], 0
	v_mfma_f32_16x16x32_bf16 v[178:181], v[134:137], v[24:27], 0
	v_mfma_f32_16x16x32_bf16 v[174:177], v[170:173], v[20:23], v[174:177]
	v_mfma_f32_16x16x32_bf16 v[178:181], v[170:173], v[28:31], v[178:181]
	s_nop 7
	ds_write2_b32 v182, v174, v178 offset0:96 offset1:112
	ds_write2_b32 v182, v175, v179 offset0:164 offset1:180
	ds_write2_b32 v182, v176, v180 offset0:232 offset1:248
	ds_write2_b32 v183, v177, v181 offset0:44 offset1:60
	v_mfma_f32_16x16x32_bf16 v[174:177], v[134:137], v[32:35], 0
	v_add_u32_e32 v182, 0x1800, v107
	v_mfma_f32_16x16x32_bf16 v[178:181], v[134:137], v[40:43], 0
	v_mfma_f32_16x16x32_bf16 v[174:177], v[170:173], v[36:39], v[174:177]
	v_mfma_f32_16x16x32_bf16 v[178:181], v[170:173], v[44:47], v[178:181]
	s_nop 7
	ds_write2_b32 v182, v174, v178 offset0:128 offset1:144
	ds_write2_b32 v182, v175, v179 offset0:196 offset1:212
	v_add_u32_e32 v178, 0x1c00, v107
	ds_write2_b32 v178, v176, v180 offset0:8 offset1:24
	ds_write2_b32 v178, v177, v181 offset0:76 offset1:92
	v_mfma_f32_16x16x32_bf16 v[174:177], v[134:137], v[48:51], 0
	v_mfma_f32_16x16x32_bf16 v[134:137], v[134:137], v[56:59], 0
	v_mfma_f32_16x16x32_bf16 v[174:177], v[170:173], v[52:55], v[174:177]
	v_mfma_f32_16x16x32_bf16 v[134:137], v[170:173], v[60:63], v[134:137]
	s_nop 7
	ds_write2_b32 v182, v174, v134 offset0:160 offset1:176
	ds_write2_b32 v182, v175, v135 offset0:228 offset1:244
	ds_write2_b32 v178, v176, v136 offset0:40 offset1:56
	ds_write2_b32 v178, v177, v137 offset0:108 offset1:124
	s_waitcnt lgkmcnt(0)
	v_add_u32_e32 v134, 0x800, v70
	ds_read2_b32 v[134:135], v134 offset0:64 offset1:132
	v_add_u32_e32 v136, 0x1800, v70
	ds_read2_b32 v[136:137], v136 offset0:128 offset1:196
	s_waitcnt lgkmcnt(1)
	v_fmamk_f32 v134, v134, 0xbfb8aa3b, v112
	v_exp_f32_e32 v134, v134
	v_fmamk_f32 v135, v135, 0xbfb8aa3b, v112
	v_exp_f32_e32 v135, v135
	s_waitcnt lgkmcnt(0)
	v_fmamk_f32 v136, v136, 0xbfb8aa3b, v65
	v_add_f32_e32 v134, 1.0, v134
	v_rcp_f32_e32 v134, v134
	v_add_f32_e32 v135, 1.0, v135
	v_exp_f32_e32 v136, v136
	v_rcp_f32_e32 v135, v135
	v_mul_f32_e32 v134, v64, v134
	v_exp_f32_e32 v134, v134
	v_add_f32_e32 v136, 1.0, v136
	v_mul_f32_e32 v135, v64, v135
	v_rcp_f32_e32 v136, v136
	v_fma_f32 v170, -v134, v134, 1.0
	v_max_f32_e32 v170, 0, v170
	v_exp_f32_e32 v135, v135
	s_nop 0
	v_sqrt_f32_e32 v170, v170
	s_nop 0
	v_fmamk_f32 v137, v137, 0xbfb8aa3b, v65
	v_exp_f32_e32 v137, v137
	s_nop 0
	v_add_f32_e32 v137, 1.0, v137
	v_rcp_f32_e32 v137, v137
	s_nop 0
	v_mul_f32_e32 v136, v136, v170
	v_fma_f32 v170, -v135, v135, 1.0
	v_max_f32_e32 v170, 0, v170
	v_mul_f32_e32 v136, v185, v136
	v_sqrt_f32_e32 v170, v170
	s_nop 0
	v_fmac_f32_e32 v136, 0, v134
	v_mul_f32_e32 v137, v137, v170
	v_mul_f32_e32 v127, v127, v137
	v_mul_f32_e32 v170, v134, v135
	v_add_u32_e32 v134, 0xa00, v70
	v_fmac_f32_e32 v127, v135, v136
	ds_read2_b32 v[134:135], v134 offset0:72 offset1:140
	v_add_u32_e32 v171, 0x1c00, v70
	ds_read2_b32 v[136:137], v171 offset0:8 offset1:76
	s_waitcnt lgkmcnt(1)
	v_fmamk_f32 v134, v134, 0xbfb8aa3b, v112
	v_exp_f32_e32 v134, v134
	s_waitcnt lgkmcnt(0)
	v_fmamk_f32 v136, v136, 0xbfb8aa3b, v65
	v_exp_f32_e32 v136, v136
	v_add_f32_e32 v134, 1.0, v134
	v_rcp_f32_e32 v134, v134
	v_add_f32_e32 v136, 1.0, v136
	v_rcp_f32_e32 v136, v136
	v_mul_f32_e32 v134, v64, v134
	v_exp_f32_e32 v134, v134
	s_nop 0
	v_fma_f32 v172, -v134, v134, 1.0
	v_max_f32_e32 v172, 0, v172
	v_sqrt_f32_e32 v172, v172
	s_nop 0
	v_mul_f32_e32 v136, v136, v172
	v_mul_f32_e32 v126, v126, v136
	v_fmac_f32_e32 v126, v134, v127
	v_mul_f32_e32 v127, v170, v134
	v_fmamk_f32 v134, v135, 0xbfb8aa3b, v112
	v_exp_f32_e32 v134, v134
	v_fmamk_f32 v135, v137, 0xbfb8aa3b, v65
	v_exp_f32_e32 v135, v135
	v_add_f32_e32 v134, 1.0, v134
	v_rcp_f32_e32 v134, v134
	v_add_f32_e32 v135, 1.0, v135
	v_rcp_f32_e32 v135, v135
	v_mul_f32_e32 v134, v64, v134
	v_exp_f32_e32 v134, v134
	s_nop 0
	v_fma_f32 v136, -v134, v134, 1.0
	v_max_f32_e32 v136, 0, v136
	v_sqrt_f32_e32 v136, v136
	s_nop 0
	v_mul_f32_e32 v135, v135, v136
	v_mul_f32_e32 v125, v125, v135
	v_fmac_f32_e32 v125, v134, v126
	v_add_u32_e32 v126, 0xc00, v70
	v_mul_f32_e32 v136, v127, v134
	ds_read2_b32 v[126:127], v126 offset0:80 offset1:148
	ds_read2_b32 v[134:135], v171 offset0:144 offset1:212
	s_waitcnt lgkmcnt(1)
	v_fmamk_f32 v126, v126, 0xbfb8aa3b, v112
	v_exp_f32_e32 v126, v126
	s_waitcnt lgkmcnt(0)
	v_fmamk_f32 v134, v134, 0xbfb8aa3b, v65
	v_exp_f32_e32 v134, v134
	v_add_f32_e32 v126, 1.0, v126
	v_rcp_f32_e32 v126, v126
	v_add_f32_e32 v134, 1.0, v134
	v_rcp_f32_e32 v134, v134
	v_mul_f32_e32 v126, v64, v126
	v_exp_f32_e32 v126, v126
	s_nop 0
	v_fma_f32 v137, -v126, v126, 1.0
	v_max_f32_e32 v137, 0, v137
	v_sqrt_f32_e32 v137, v137
	s_nop 0
	v_mul_f32_e32 v134, v134, v137
	v_mul_f32_e32 v124, v124, v134
	v_fmac_f32_e32 v124, v126, v125
	v_mul_f32_e32 v125, v136, v126
	v_fmamk_f32 v126, v127, 0xbfb8aa3b, v112
	v_exp_f32_e32 v126, v126
	v_fmamk_f32 v127, v135, 0xbfb8aa3b, v65
	v_exp_f32_e32 v127, v127
	v_add_f32_e32 v126, 1.0, v126
	v_rcp_f32_e32 v126, v126
	v_add_f32_e32 v127, 1.0, v127
	v_rcp_f32_e32 v127, v127
	v_mul_f32_e32 v126, v64, v126
	v_exp_f32_e32 v126, v126
	s_nop 0
	v_fma_f32 v134, -v126, v126, 1.0
	v_max_f32_e32 v134, 0, v134
	v_sqrt_f32_e32 v134, v134
	s_nop 0
	v_mul_f32_e32 v127, v127, v134
	v_mul_f32_e32 v123, v123, v127
	v_fmac_f32_e32 v123, v126, v124
	v_add_u32_e32 v124, 0xe00, v70
	v_mul_f32_e32 v134, v125, v126
	ds_read2_b32 v[124:125], v124 offset0:88 offset1:156
	v_add_u32_e32 v135, 0x2000, v70
	ds_read2_b32 v[126:127], v135 offset0:24 offset1:92
	s_waitcnt lgkmcnt(1)
	v_fmamk_f32 v124, v124, 0xbfb8aa3b, v112
	v_exp_f32_e32 v124, v124
	s_waitcnt lgkmcnt(0)
	v_fmamk_f32 v126, v126, 0xbfb8aa3b, v65
	v_exp_f32_e32 v126, v126
	v_add_f32_e32 v124, 1.0, v124
	v_rcp_f32_e32 v124, v124
	v_add_f32_e32 v126, 1.0, v126
	v_rcp_f32_e32 v126, v126
	v_mul_f32_e32 v124, v64, v124
	v_exp_f32_e32 v124, v124
	s_nop 0
	v_fma_f32 v136, -v124, v124, 1.0
	v_max_f32_e32 v136, 0, v136
	v_sqrt_f32_e32 v136, v136
	s_nop 0
	v_mul_f32_e32 v126, v126, v136
	v_mul_f32_e32 v122, v122, v126
	v_fmac_f32_e32 v122, v124, v123
	v_mul_f32_e32 v123, v134, v124
	v_fmamk_f32 v124, v125, 0xbfb8aa3b, v112
	v_exp_f32_e32 v124, v124
	v_fmamk_f32 v125, v127, 0xbfb8aa3b, v65
	v_exp_f32_e32 v125, v125
	v_add_f32_e32 v124, 1.0, v124
	v_rcp_f32_e32 v124, v124
	v_add_f32_e32 v125, 1.0, v125
	v_rcp_f32_e32 v125, v125
	v_mul_f32_e32 v124, v64, v124
	v_exp_f32_e32 v124, v124
	s_nop 0
	v_fma_f32 v126, -v124, v124, 1.0
	v_max_f32_e32 v126, 0, v126
	v_sqrt_f32_e32 v126, v126
	s_nop 0
	v_mul_f32_e32 v125, v125, v126
	v_mul_f32_e32 v121, v121, v125
	v_fmac_f32_e32 v121, v124, v122
	v_add_u32_e32 v122, 0x1000, v70
	v_mul_f32_e32 v126, v123, v124
	ds_read2_b32 v[122:123], v122 offset0:96 offset1:164
	ds_read2_b32 v[124:125], v135 offset0:160 offset1:228
	s_waitcnt lgkmcnt(1)
	v_fmamk_f32 v122, v122, 0xbfb8aa3b, v112
	v_exp_f32_e32 v122, v122
	s_waitcnt lgkmcnt(0)
	v_fmamk_f32 v124, v124, 0xbfb8aa3b, v65
	v_exp_f32_e32 v124, v124
	v_add_f32_e32 v122, 1.0, v122
	v_rcp_f32_e32 v122, v122
	v_add_f32_e32 v124, 1.0, v124
	v_rcp_f32_e32 v124, v124
	v_mul_f32_e32 v122, v64, v122
	v_exp_f32_e32 v122, v122
	s_nop 0
	v_fma_f32 v127, -v122, v122, 1.0
	v_max_f32_e32 v127, 0, v127
	v_sqrt_f32_e32 v127, v127
	s_nop 0
	v_mul_f32_e32 v124, v124, v127
	v_mul_f32_e32 v120, v120, v124
	v_fmac_f32_e32 v120, v122, v121
	v_mul_f32_e32 v121, v126, v122
	v_fmamk_f32 v122, v123, 0xbfb8aa3b, v112
	v_exp_f32_e32 v122, v122
	v_fmamk_f32 v123, v125, 0xbfb8aa3b, v65
	v_exp_f32_e32 v123, v123
	v_add_f32_e32 v122, 1.0, v122
	v_rcp_f32_e32 v122, v122
	v_add_f32_e32 v123, 1.0, v123
	v_rcp_f32_e32 v123, v123
	v_mul_f32_e32 v122, v64, v122
	v_exp_f32_e32 v122, v122
	s_nop 0
	v_fma_f32 v124, -v122, v122, 1.0
	v_max_f32_e32 v124, 0, v124
	v_sqrt_f32_e32 v124, v124
	s_nop 0
	v_mul_f32_e32 v123, v123, v124
	v_mul_f32_e32 v119, v119, v123
	v_fmac_f32_e32 v119, v122, v120
	v_add_u32_e32 v120, 0x1200, v70
	v_mul_f32_e32 v124, v121, v122
	ds_read2_b32 v[120:121], v120 offset0:104 offset1:172
	v_add_u32_e32 v125, 0x2400, v70
	ds_read2_b32 v[122:123], v125 offset0:40 offset1:108
	s_waitcnt lgkmcnt(1)
	v_fmamk_f32 v120, v120, 0xbfb8aa3b, v112
	v_exp_f32_e32 v120, v120
	s_waitcnt lgkmcnt(0)
	v_fmamk_f32 v122, v122, 0xbfb8aa3b, v65
	v_exp_f32_e32 v122, v122
	v_add_f32_e32 v120, 1.0, v120
	v_rcp_f32_e32 v120, v120
	v_add_f32_e32 v122, 1.0, v122
	v_rcp_f32_e32 v122, v122
	v_mul_f32_e32 v120, v64, v120
	v_exp_f32_e32 v120, v120
	s_nop 0
	v_fma_f32 v126, -v120, v120, 1.0
	v_max_f32_e32 v126, 0, v126
	v_sqrt_f32_e32 v126, v126
	s_nop 0
	v_mul_f32_e32 v122, v122, v126
	v_mul_f32_e32 v118, v118, v122
	v_fmac_f32_e32 v118, v120, v119
	v_mul_f32_e32 v119, v124, v120
	v_fmamk_f32 v120, v121, 0xbfb8aa3b, v112
	v_exp_f32_e32 v120, v120
	v_fmamk_f32 v121, v123, 0xbfb8aa3b, v65
	v_exp_f32_e32 v121, v121
	v_add_f32_e32 v120, 1.0, v120
	v_rcp_f32_e32 v120, v120
	v_add_f32_e32 v121, 1.0, v121
	v_rcp_f32_e32 v121, v121
	v_mul_f32_e32 v120, v64, v120
	v_exp_f32_e32 v120, v120
	s_nop 0
	v_fma_f32 v122, -v120, v120, 1.0
	v_max_f32_e32 v122, 0, v122
	v_sqrt_f32_e32 v122, v122
	s_nop 0
	v_mul_f32_e32 v121, v121, v122
	v_mul_f32_e32 v117, v117, v121
	v_fmac_f32_e32 v117, v120, v118
	v_add_u32_e32 v118, 0x1400, v70
	v_mul_f32_e32 v122, v119, v120
	ds_read2_b32 v[118:119], v118 offset0:112 offset1:180
	ds_read2_b32 v[120:121], v125 offset0:176 offset1:244
	s_waitcnt lgkmcnt(1)
	v_fmamk_f32 v118, v118, 0xbfb8aa3b, v112
	v_exp_f32_e32 v118, v118
	s_waitcnt lgkmcnt(0)
	v_fmamk_f32 v120, v120, 0xbfb8aa3b, v65
	v_exp_f32_e32 v120, v120
	v_add_f32_e32 v118, 1.0, v118
	v_rcp_f32_e32 v118, v118
	v_add_f32_e32 v120, 1.0, v120
	v_rcp_f32_e32 v120, v120
	v_mul_f32_e32 v118, v64, v118
	v_exp_f32_e32 v118, v118
	s_nop 0
	v_fma_f32 v123, -v118, v118, 1.0
	v_max_f32_e32 v123, 0, v123
	v_sqrt_f32_e32 v123, v123
	s_nop 0
	v_mul_f32_e32 v120, v120, v123
	v_mul_f32_e32 v116, v116, v120
	v_fmac_f32_e32 v116, v118, v117
	v_mul_f32_e32 v117, v122, v118
	v_fmamk_f32 v118, v119, 0xbfb8aa3b, v112
	v_exp_f32_e32 v118, v118
	v_fmamk_f32 v119, v121, 0xbfb8aa3b, v65
	v_exp_f32_e32 v119, v119
	v_add_f32_e32 v118, 1.0, v118
	v_rcp_f32_e32 v118, v118
	v_add_f32_e32 v119, 1.0, v119
	v_rcp_f32_e32 v119, v119
	v_mul_f32_e32 v118, v64, v118
	v_exp_f32_e32 v118, v118
	s_nop 0
	v_fma_f32 v120, -v118, v118, 1.0
	v_max_f32_e32 v120, 0, v120
	v_sqrt_f32_e32 v120, v120
	s_nop 0
	v_mul_f32_e32 v119, v119, v120
	v_mul_f32_e32 v115, v115, v119
	v_fmac_f32_e32 v115, v118, v116
	v_add_u32_e32 v116, 0x1600, v70
	v_mul_f32_e32 v120, v117, v118
	ds_read2_b32 v[116:117], v116 offset0:120 offset1:188
	v_add_u32_e32 v118, 0x2800, v70
	ds_read2_b32 v[118:119], v118 offset0:56 offset1:124
	s_waitcnt lgkmcnt(1)
	v_fmamk_f32 v116, v116, 0xbfb8aa3b, v112
	v_exp_f32_e32 v116, v116
	s_waitcnt lgkmcnt(0)
	v_fmamk_f32 v118, v118, 0xbfb8aa3b, v65
	v_exp_f32_e32 v118, v118
	v_add_f32_e32 v116, 1.0, v116
	v_rcp_f32_e32 v116, v116
	v_add_f32_e32 v118, 1.0, v118
	v_rcp_f32_e32 v118, v118
	v_mul_f32_e32 v116, v64, v116
	v_exp_f32_e32 v116, v116
	s_nop 0
	v_fma_f32 v121, -v116, v116, 1.0
	v_max_f32_e32 v121, 0, v121
	v_sqrt_f32_e32 v121, v121
	s_nop 0
	v_mul_f32_e32 v118, v118, v121
	v_mul_f32_e32 v114, v114, v118
	v_fmac_f32_e32 v114, v116, v115
	v_mul_f32_e32 v115, v120, v116
	v_fmamk_f32 v116, v117, 0xbfb8aa3b, v112
	v_exp_f32_e32 v116, v116
	v_fmamk_f32 v117, v119, 0xbfb8aa3b, v65
	v_exp_f32_e32 v117, v117
	v_add_f32_e32 v116, 1.0, v116
	v_rcp_f32_e32 v116, v116
	v_add_f32_e32 v117, 1.0, v117
	v_rcp_f32_e32 v117, v117
	v_mul_f32_e32 v116, v64, v116
	v_exp_f32_e32 v116, v116
	s_nop 0
	v_fma_f32 v118, -v116, v116, 1.0
	v_max_f32_e32 v118, 0, v118
	v_sqrt_f32_e32 v118, v118
	s_nop 0
	v_mul_f32_e32 v117, v117, v118
	v_mul_f32_e32 v113, v113, v117
	v_fmac_f32_e32 v113, v116, v114
	v_mul_f32_e32 v114, v115, v116
	v_add_u32_e32 v115, s14, v67
	s_andn2_b64 vcc, exec, s[50:51]
	ds_write2st64_b32 v115, v114, v113 offset1:1
	s_waitcnt lgkmcnt(0)
	s_barrier
	s_cbranch_vccnz .LBB0_122
	ds_read2st64_b32 v[114:115], v67 offset1:1
	ds_read2st64_b32 v[116:117], v67 offset0:2 offset1:3
	s_ashr_i32 s5, s4, 31
	s_lshl_b64 s[0:1], s[4:5], 14
	v_readlane_b32 s4, v243, 35
	s_waitcnt lgkmcnt(1)
	v_fma_f32 v113, 0, v114, v115
	s_waitcnt lgkmcnt(0)
	v_mul_f32_e32 v118, v114, v116
	ds_read2st64_b32 v[114:115], v67 offset0:4 offset1:5
	v_fmac_f32_e32 v117, v113, v116
	v_readlane_b32 s5, v243, 36
	s_add_u32 s0, s4, s0
	s_addc_u32 s1, s5, s1
	s_waitcnt lgkmcnt(0)
	v_fmac_f32_e32 v115, v117, v114
	ds_read2st64_b32 v[116:117], v67 offset0:6 offset1:7
	v_mul_f32_e32 v113, v118, v114
	s_lshl_b32 s4, s17, 2
	s_add_u32 s0, s0, s4
	s_addc_u32 s1, s1, 0
	s_waitcnt lgkmcnt(0)
	v_fmac_f32_e32 v117, v115, v116
	ds_read2st64_b32 v[114:115], v67 offset0:8 offset1:9
	v_mul_f32_e32 v113, v113, v116
	s_waitcnt lgkmcnt(0)
	v_fmac_f32_e32 v115, v117, v114
	ds_read2st64_b32 v[116:117], v67 offset0:10 offset1:11
	v_mul_f32_e32 v113, v113, v114
	s_waitcnt lgkmcnt(0)
	v_fmac_f32_e32 v117, v115, v116
	ds_read2st64_b32 v[114:115], v67 offset0:12 offset1:13
	v_mul_f32_e32 v113, v113, v116
	s_waitcnt lgkmcnt(0)
	v_fmac_f32_e32 v115, v117, v114
	ds_read2st64_b32 v[116:117], v67 offset0:14 offset1:15
	v_mul_f32_e32 v113, v113, v114
	s_waitcnt lgkmcnt(0)
	v_mul_f32_e32 v113, v113, v116
	v_fmac_f32_e32 v117, v115, v116
	global_store_dword v141, v113, s[0:1]
	global_store_dword v141, v117, s[0:1] offset:256
	s_branch .LBB0_122
